# XCD-local tile order also in P1 (n-quarter per XCD) and P4c (n-half per XCD)
# speedup vs baseline: 1.0199x; 1.0035x over previous
; __device__ __forceinline__ void phase1(const Params& p, char* smem) {
;     ...
;   for (int it = blockIdx.x; it < NTILES; it += gridDim.x) {
;     const int nt = it & 31, mt = it >> 5;
;     const int m0 = mt * 128, n0 = nt * 128;
;     f32x16 acc[2][2]; zero_acc(acc);
;     gemm_mainloop_dma(acc, H + (size_t)m0 * 1024, 1024, WT + (size_t)n0 * 1024, 1024, 1024, smem);
.LBB0_173:
	s_and_b32 s32, s35, 0xffffff00
	s_lshr_b32 s0, s35, 3
	s_and_b32 s0, s0, 7
	s_or_b32 s32, s32, s0
	s_and_b32 s0, s35, 3
	s_lshl_b32 s0, s0, 3
	s_or_b32 s32, s32, s0
	s_lshr_b32 s0, s35, 6
	s_and_b32 s0, s0, 3
	s_lshl_b32 s0, s0, 5
	s_or_b32 s32, s32, s0
	s_lshr_b32 s0, s35, 2
	s_and_b32 s0, s0, 1
	s_lshl_b32 s0, s0, 7
	s_or_b32 s32, s32, s0
	s_cmpk_lt_i32 s35, 0x1000
	s_cselect_b32 s32, s32, s35
	s_and_b32 s0, s32, 31
	s_lshl_b32 s2, s0, 18
	v_lshl_add_u64 v[54:55], v[20:21], 0, s[2:3]
	v_lshl_add_u64 v[56:57], v[22:23], 0, s[2:3]
	v_lshl_add_u64 v[58:59], v[24:25], 0, s[2:3]
	v_lshl_add_u64 v[60:61], v[26:27], 0, s[2:3]
	v_lshl_add_u64 v[62:63], v[28:29], 0, s[2:3]
	v_lshl_add_u64 v[64:65], v[30:31], 0, s[2:3]
	v_lshl_add_u64 v[66:67], v[32:33], 0, s[2:3]
	v_or_b32_e32 v68, s2, v34
	s_lshl_b32 s2, s32, 2
	s_lshl_b32 s0, s32, 2
	s_and_b32 s0, s0, 0xffffff80
	s_and_b32 s16, s2, 0xffffff80
	s_ashr_i32 s1, s0, 31
	s_ashr_i32 s17, s16, 31
	s_lshl_b64 s[0:1], s[0:1], 11
	s_and_b32 s6, s32, 31
	s_lshl_b64 s[4:5], s[16:17], 11
	s_add_u32 s4, s38, s4
	s_addc_u32 s5, s39, s5
	s_lshl_b32 s2, s6, 18
	s_add_u32 s18, s80, s2
	v_lshl_add_u64 v[70:71], s[4:5], 0, v[0:1]
	v_readfirstlane_b32 s2, v118
	s_addc_u32 s19, s81, 0
	v_lshl_add_u64 v[70:71], v[70:71], 0, v[36:37]
	s_mov_b32 m0, s2
	s_barrier
	global_load_lds_dwordx4 v[70:71], off
	v_lshl_add_u64 v[70:71], s[18:19], 0, v[0:1]
	v_readfirstlane_b32 s2, v241
	v_lshl_add_u64 v[70:71], v[70:71], 0, v[36:37]
	s_mov_b32 m0, s2
	v_readfirstlane_b32 s2, v119
	global_load_lds_dwordx4 v[70:71], off
	v_lshl_add_u64 v[70:71], s[4:5], 0, v[4:5]
	v_lshl_add_u64 v[70:71], v[70:71], 0, v[38:39]
	s_mov_b32 m0, s2
	v_readfirstlane_b32 s2, v242
	global_load_lds_dwordx4 v[70:71], off
	v_lshl_add_u64 v[70:71], s[18:19], 0, v[4:5]
	v_lshl_add_u64 v[70:71], v[70:71], 0, v[38:39]
	s_mov_b32 m0, s2
	v_readfirstlane_b32 s2, v120
	global_load_lds_dwordx4 v[70:71], off
	v_lshl_add_u64 v[70:71], s[4:5], 0, v[6:7]
	v_lshl_add_u64 v[70:71], v[70:71], 0, v[40:41]
	s_mov_b32 m0, s2
	v_readfirstlane_b32 s2, v243
	global_load_lds_dwordx4 v[70:71], off
	v_lshl_add_u64 v[70:71], s[18:19], 0, v[6:7]
	v_lshl_add_u64 v[70:71], v[70:71], 0, v[40:41]
	s_mov_b32 m0, s2
	v_readfirstlane_b32 s2, v121
	global_load_lds_dwordx4 v[70:71], off
	v_lshl_add_u64 v[70:71], s[4:5], 0, v[8:9]
	v_lshl_add_u64 v[70:71], v[70:71], 0, v[42:43]
	s_mov_b32 m0, s2
	v_readfirstlane_b32 s2, v244
	global_load_lds_dwordx4 v[70:71], off
	v_lshl_add_u64 v[70:71], s[18:19], 0, v[8:9]
	v_lshl_add_u64 v[70:71], v[70:71], 0, v[42:43]
	s_mov_b32 m0, s2
	v_readfirstlane_b32 s2, v122
	global_load_lds_dwordx4 v[70:71], off
	v_lshl_add_u64 v[70:71], s[4:5], 0, v[10:11]
	v_lshl_add_u64 v[70:71], v[70:71], 0, v[44:45]
	s_mov_b32 m0, s2
	v_readfirstlane_b32 s2, v245
	global_load_lds_dwordx4 v[70:71], off
	v_lshl_add_u64 v[70:71], s[18:19], 0, v[10:11]
	v_lshl_add_u64 v[70:71], v[70:71], 0, v[44:45]
	s_mov_b32 m0, s2
	v_readfirstlane_b32 s2, v123
	global_load_lds_dwordx4 v[70:71], off
	v_lshl_add_u64 v[70:71], s[4:5], 0, v[12:13]
	v_lshl_add_u64 v[70:71], v[70:71], 0, v[46:47]
	s_mov_b32 m0, s2
	v_readfirstlane_b32 s2, v246
	global_load_lds_dwordx4 v[70:71], off
	v_lshl_add_u64 v[70:71], s[18:19], 0, v[12:13]
	v_lshl_add_u64 v[70:71], v[70:71], 0, v[46:47]
	s_mov_b32 m0, s2
	v_readfirstlane_b32 s2, v124
	global_load_lds_dwordx4 v[70:71], off
	v_lshl_add_u64 v[70:71], s[4:5], 0, v[14:15]
	v_lshl_add_u64 v[70:71], v[70:71], 0, v[48:49]
	s_mov_b32 m0, s2
	v_readfirstlane_b32 s2, v247
	global_load_lds_dwordx4 v[70:71], off
	v_lshl_add_u64 v[70:71], s[18:19], 0, v[14:15]
	v_lshl_add_u64 v[70:71], v[70:71], 0, v[48:49]
	s_mov_b32 m0, s2
	v_readfirstlane_b32 s2, v125
	global_load_lds_dwordx4 v[70:71], off
	v_lshl_add_u64 v[70:71], s[4:5], 0, v[16:17]
	v_lshl_add_u64 v[70:71], v[70:71], 0, v[50:51]
	s_mov_b32 m0, s2
	v_readfirstlane_b32 s2, v248
	global_load_lds_dwordx4 v[70:71], off
	v_lshl_add_u64 v[70:71], s[18:19], 0, v[16:17]
	v_lshl_add_u64 v[70:71], v[70:71], 0, v[50:51]
	s_mov_b32 m0, s2
	v_mov_b32_e32 v69, v35
	global_load_lds_dwordx4 v[70:71], off
	s_waitcnt vmcnt(0)
	v_lshl_add_u64 v[70:71], v[20:21], 0, s[0:1]
	v_lshl_add_u64 v[72:73], v[22:23], 0, s[0:1]
	v_lshl_add_u64 v[74:75], v[24:25], 0, s[0:1]
	v_lshl_add_u64 v[76:77], v[26:27], 0, s[0:1]
	v_lshl_add_u64 v[78:79], v[28:29], 0, s[0:1]
	v_lshl_add_u64 v[80:81], v[30:31], 0, s[0:1]
	v_lshl_add_u64 v[82:83], v[32:33], 0, s[0:1]
	v_mov_b32_e32 v85, s1
	v_or_b32_e32 v84, s0, v34
	s_mov_b32 s2, 0
	v_accvgpr_write_b32 a0, 0
	v_accvgpr_mov_b32 a1, a119
	v_accvgpr_mov_b32 a2, a118
	v_accvgpr_mov_b32 a3, a117
	v_accvgpr_mov_b32 a4, a116
	v_accvgpr_mov_b32 a5, a115
	v_accvgpr_mov_b32 a6, a114
	v_accvgpr_mov_b32 a7, a113
	v_accvgpr_mov_b32 a8, a112
	v_accvgpr_mov_b32 a9, a111
	v_accvgpr_mov_b32 a10, a110
	v_accvgpr_mov_b32 a11, a109
	v_accvgpr_mov_b32 a12, a108
	v_accvgpr_mov_b32 a13, a107
	v_accvgpr_mov_b32 a14, a106
	v_accvgpr_mov_b32 a15, a105
	v_accvgpr_write_b32 a16, 0
	v_accvgpr_mov_b32 a17, a104
	v_accvgpr_mov_b32 a18, a103
	v_accvgpr_mov_b32 a19, a102
	v_accvgpr_mov_b32 a20, a101
	v_accvgpr_mov_b32 a21, a100
	v_accvgpr_mov_b32 a22, a99
	v_accvgpr_mov_b32 a23, a98
	v_accvgpr_mov_b32 a24, a97
	v_accvgpr_mov_b32 a25, a96
	v_accvgpr_mov_b32 a26, a95
	v_accvgpr_mov_b32 a27, a94
	v_accvgpr_mov_b32 a28, a93
	v_accvgpr_mov_b32 a29, a92
	v_accvgpr_mov_b32 a30, a91
	v_accvgpr_mov_b32 a31, a90
	v_accvgpr_write_b32 a32, 0
	v_accvgpr_mov_b32 a33, a89
	v_accvgpr_mov_b32 a34, a88
	v_accvgpr_mov_b32 a35, a87
	v_accvgpr_mov_b32 a36, a86
	v_accvgpr_mov_b32 a37, a85
	v_accvgpr_mov_b32 a38, a84
	v_accvgpr_mov_b32 a39, a83
	v_accvgpr_mov_b32 a40, a82
	v_accvgpr_mov_b32 a41, a81
	v_accvgpr_mov_b32 a42, a80
	v_accvgpr_mov_b32 a43, a79
	v_accvgpr_mov_b32 a44, a78
	v_accvgpr_mov_b32 a45, a77
	v_accvgpr_mov_b32 a46, a76
	v_accvgpr_mov_b32 a47, a75
	v_accvgpr_write_b32 a48, 0
	v_accvgpr_mov_b32 a49, a74
	v_accvgpr_mov_b32 a50, a73
	v_accvgpr_mov_b32 a51, a72
	v_accvgpr_mov_b32 a52, a71
	v_accvgpr_mov_b32 a53, a70
	v_accvgpr_mov_b32 a54, a69
	v_accvgpr_mov_b32 a55, a68
	v_accvgpr_mov_b32 a56, a67
	v_accvgpr_mov_b32 a57, a66
	v_accvgpr_mov_b32 a58, a65
	v_accvgpr_mov_b32 a59, a64
	v_accvgpr_write_b32 a60, 0
	v_accvgpr_write_b32 a61, 0
	v_accvgpr_write_b32 a62, 0
	v_accvgpr_write_b32 a63, 0
	s_waitcnt vmcnt(0) lgkmcnt(0)
	s_barrier
	s_branch .LBB0_175

; __device__ __forceinline__ u16 f2bf(float f) { return (u16)(pack2(f, f) & 0xffffu); }
; __device__ __forceinline__ float sigmoidf_(float x) { return __builtin_amdgcn_rcpf(1.f + __expf(-x)); }
; __device__ __forceinline__ float siluf_(float x) { return x * __builtin_amdgcn_rcpf(1.f + __expf(-x)); }
; __device__ __forceinline__ int rowmap(int e, int lane) { return (e & 3) + 8 * (e >> 2) + 4 * (lane >> 5); }
; __device__ __forceinline__ void phase1(const Params& p, char* smem) {
;     ...
;     const int seg = nt >> 2, cb = (nt & 3) * 128;
;     if (seg == 1) {
;       float* T32 = (float*)smem;
; #pragma unroll
;       for (int i = 0; i < 2; i++)
; #pragma unroll
;         for (int j = 0; j < 2; j++) {
;           const int cl = wn * 64 + j * 32 + (lane & 31);
;           const float p0 = p.lb_param[cb + cl], p1 = p.lb_param[512 + cb + cl];
;           const float lb = 1.f / (1.f + __expf(p1 - p0));
; #pragma unroll
;           for (int e = 0; e < 16; e++) {
;             const float f = lb + (1.f - lb) * sigmoidf_(acc[i][j][e]);
;             T32[(wm * 64 + i * 32 + rowmap(e, lane)) * 132 + cl] = __logf(f);
;           }
;         }
;       __syncthreads();
; #pragma unroll
;       for (int q = 0; q < 16; q++) {
;         const int idx = tid + 256 * q, row = idx >> 5, c4 = idx & 31;
;         *(float4*)(LOGF + (size_t)(m0 + row) * 512 + cb + c4 * 4) = *(const float4*)&T32[row * 132 + c4 * 4];
;       }
;     } else {
;       u16* T = (u16*)smem;
;       const bool act = (seg == 0 || seg == 3 || seg == 7);
; #pragma unroll
;       for (int i = 0; i < 2; i++)
; #pragma unroll
;         for (int j = 0; j < 2; j++) {
;           const int cl = wn * 64 + j * 32 + (lane & 31);
; #pragma unroll
;           for (int e = 0; e < 16; e++) {
;             const float v = acc[i][j][e];
;             const int rl = wm * 64 + i * 32 + rowmap(e, lane);
;             T[rl * 136 + cl] = f2bf(act ? siluf_(v) : v);
;             if (seg >= 4 && seg <= 6) {
;               const int row = m0 + rl; const int ch = (seg - 4) * 512 + cb + cl;
;               if (row < NTP) { int t = row & 2047; if (t >= 2045) p.out[OUT_CP + ((size_t)(row >> 11) * 3 + (t - 2045)) * 1536 + ch] = v; }
;               else { int rs = row - NTP; int t = rs & 3; if (t >= 1) p.out[OUT_CS + ((size_t)(rs >> 2) * 3 + (t - 1)) * 1536 + ch] = v; }
;             }
.LBB0_177:
	s_lshl_b32 s0, s32, 7
	s_lshr_b32 s17, s6, 2
	s_and_b32 s2, s0, 0x180
	v_accvgpr_read_b32 v100, a0
	v_accvgpr_read_b32 v99, a1
	v_accvgpr_read_b32 v98, a2
	v_accvgpr_read_b32 v97, a3
	v_accvgpr_read_b32 v96, a4
	v_accvgpr_read_b32 v95, a5
	v_accvgpr_read_b32 v94, a6
	v_accvgpr_read_b32 v93, a7
	v_accvgpr_read_b32 v92, a8
	v_accvgpr_read_b32 v91, a9
	v_accvgpr_read_b32 v90, a10
	v_accvgpr_read_b32 v89, a11
	v_accvgpr_read_b32 v88, a12
	v_accvgpr_read_b32 v87, a13
	v_accvgpr_read_b32 v86, a14
	v_accvgpr_read_b32 v19, a15
	v_accvgpr_read_b32 v116, a16
	v_accvgpr_read_b32 v115, a17
	v_accvgpr_read_b32 v114, a18
	v_accvgpr_read_b32 v113, a19
	v_accvgpr_read_b32 v112, a20
	v_accvgpr_read_b32 v111, a21
	v_accvgpr_read_b32 v110, a22
	v_accvgpr_read_b32 v109, a23
	v_accvgpr_read_b32 v108, a24
	v_accvgpr_read_b32 v107, a25
	v_accvgpr_read_b32 v106, a26
	v_accvgpr_read_b32 v105, a27
	v_accvgpr_read_b32 v104, a28
	v_accvgpr_read_b32 v103, a29
	v_accvgpr_read_b32 v102, a30
	v_accvgpr_read_b32 v101, a31
	v_accvgpr_read_b32 v190, a32
	v_accvgpr_read_b32 v189, a33
	v_accvgpr_read_b32 v188, a34
	v_accvgpr_read_b32 v187, a35
	v_accvgpr_read_b32 v186, a36
	v_accvgpr_read_b32 v185, a37
	v_accvgpr_read_b32 v184, a38
	v_accvgpr_read_b32 v183, a39
	v_accvgpr_read_b32 v182, a40
	v_accvgpr_read_b32 v181, a41
	v_accvgpr_read_b32 v180, a42
	v_accvgpr_read_b32 v179, a43
	v_accvgpr_read_b32 v178, a44
	v_accvgpr_read_b32 v177, a45
	v_accvgpr_read_b32 v176, a46
	v_accvgpr_read_b32 v117, a47
	v_accvgpr_read_b32 v215, a48
	v_accvgpr_read_b32 v210, a49
	v_accvgpr_read_b32 v208, a50
	v_accvgpr_read_b32 v206, a51
	v_accvgpr_read_b32 v204, a52
	v_accvgpr_read_b32 v203, a53
	v_accvgpr_read_b32 v202, a54
	v_accvgpr_read_b32 v200, a55
	v_accvgpr_read_b32 v198, a56
	v_accvgpr_read_b32 v197, a57
	v_accvgpr_read_b32 v196, a58
	v_accvgpr_read_b32 v195, a59
	v_accvgpr_read_b32 v194, a60
	v_accvgpr_read_b32 v193, a61
	v_accvgpr_read_b32 v192, a62
	v_accvgpr_read_b32 v191, a63
	s_cmp_lg_u32 s17, 1
	s_mov_b64 s[0:1], -1
	s_cbranch_scc0 .LBB0_711
	s_cmp_lt_u32 s17, 4
	s_cbranch_scc1 .Lp1_fast
	s_cmp_gt_u32 s17, 6
	s_cbranch_scc1 .Lp1_fast
	s_cmp_ge_u32 s16, 0x4000
	s_cbranch_scc1 .Lp1_generic
	s_and_b32 s0, s16, 0x780
	s_cmp_eq_u32 s0, 0x780
	s_cbranch_scc1 .Lp1_generic

; __device__ __forceinline__ void phase4c(const Params& p, char* smem) {
;     ...
;   for (int it = blockIdx.x; it < 132 * 16; it += gridDim.x) {
;     const int nt = it & 15, mt = it >> 4;
;     const int m0 = mt * 128, n0 = nt * 128;
;     f32x16 acc[2][2]; zero_acc(acc);
;     gemm_mainloop_dma(acc, (const u16*)(ws + OFF_X1B) + (size_t)m0 * 1024, 1024, (const u16*)(ws + OFF_WT_Q) + (size_t)n0 * 1024, 1024, 1024, smem);
.LBB0_1416:
	s_and_b32 s32, s29, 0xffffff00
	s_lshr_b32 s0, s29, 3
	s_and_b32 s0, s0, 7
	s_or_b32 s32, s32, s0
	s_and_b32 s0, s29, 1
	s_lshl_b32 s0, s0, 3
	s_or_b32 s32, s32, s0
	s_lshr_b32 s0, s29, 6
	s_and_b32 s0, s0, 3
	s_lshl_b32 s0, s0, 4
	s_or_b32 s32, s32, s0
	s_lshr_b32 s0, s29, 1
	s_and_b32 s0, s0, 3
	s_lshl_b32 s0, s0, 6
	s_or_b32 s32, s32, s0
	s_cmpk_lt_i32 s29, 0x800
	s_cselect_b32 s32, s32, s29
	s_and_b32 s0, s32, 15
	s_lshl_b32 s20, s32, 3
	s_lshl_b32 s2, s0, 18
	s_lshl_b32 s0, s32, 3
	s_and_b32 s0, s0, 0xffffff80
	s_and_b32 s20, s20, 0xffffff80
	s_ashr_i32 s1, s0, 31
	s_ashr_i32 s21, s20, 31
	v_lshl_add_u64 v[0:1], v[24:25], 0, s[2:3]
	v_lshl_add_u64 v[2:3], v[26:27], 0, s[2:3]
	v_lshl_add_u64 v[56:57], v[28:29], 0, s[2:3]
	v_lshl_add_u64 v[58:59], v[30:31], 0, s[2:3]
	v_lshl_add_u64 v[60:61], v[32:33], 0, s[2:3]
	v_lshl_add_u64 v[62:63], v[34:35], 0, s[2:3]
	v_lshl_add_u64 v[64:65], v[36:37], 0, s[2:3]
	v_or_b32_e32 v66, s2, v38
	s_lshl_b64 s[0:1], s[0:1], 11
	s_and_b32 s2, s32, 15
	s_lshl_b64 s[34:35], s[20:21], 11
	s_add_u32 s34, s17, s34
	s_addc_u32 s35, s19, s35
	s_lshl_b32 s21, s2, 18
	s_add_u32 s36, s22, s21
	v_lshl_add_u64 v[8:9], s[34:35], 0, v[4:5]
	v_readfirstlane_b32 s21, v116
	s_addc_u32 s37, s23, 0
	v_lshl_add_u64 v[8:9], v[8:9], 0, v[40:41]
	s_mov_b32 m0, s21
	s_barrier
	global_load_lds_dwordx4 v[8:9], off
	v_lshl_add_u64 v[8:9], s[36:37], 0, v[4:5]
	v_readfirstlane_b32 s21, v196
	v_lshl_add_u64 v[8:9], v[8:9], 0, v[40:41]
	s_mov_b32 m0, s21
	v_readfirstlane_b32 s21, v117
	global_load_lds_dwordx4 v[8:9], off
	v_lshl_add_u64 v[8:9], s[34:35], 0, v[180:181]
	v_lshl_add_u64 v[8:9], v[8:9], 0, v[42:43]
	s_mov_b32 m0, s21
	v_readfirstlane_b32 s21, v197
	global_load_lds_dwordx4 v[8:9], off
	v_lshl_add_u64 v[8:9], s[36:37], 0, v[180:181]
	v_accvgpr_read_b32 v10, a142
	v_lshl_add_u64 v[8:9], v[8:9], 0, v[42:43]
	s_mov_b32 m0, s21
	v_accvgpr_read_b32 v11, a143
	global_load_lds_dwordx4 v[8:9], off
	v_lshl_add_u64 v[8:9], s[34:35], 0, v[10:11]
	v_readfirstlane_b32 s21, v118
	v_lshl_add_u64 v[8:9], v[8:9], 0, v[44:45]
	s_mov_b32 m0, s21
	v_readfirstlane_b32 s21, v198
	global_load_lds_dwordx4 v[8:9], off
	v_lshl_add_u64 v[8:9], s[36:37], 0, v[10:11]
	v_lshl_add_u64 v[8:9], v[8:9], 0, v[44:45]
	s_mov_b32 m0, s21
	v_readfirstlane_b32 s21, v119
	global_load_lds_dwordx4 v[8:9], off
	v_lshl_add_u64 v[8:9], s[34:35], 0, v[12:13]
	v_lshl_add_u64 v[8:9], v[8:9], 0, v[46:47]
	s_mov_b32 m0, s21
	v_readfirstlane_b32 s21, v199
	global_load_lds_dwordx4 v[8:9], off
	v_lshl_add_u64 v[8:9], s[36:37], 0, v[12:13]
	v_lshl_add_u64 v[8:9], v[8:9], 0, v[46:47]
	s_mov_b32 m0, s21
	v_readfirstlane_b32 s21, v120
	global_load_lds_dwordx4 v[8:9], off
	v_lshl_add_u64 v[8:9], s[34:35], 0, v[14:15]
	v_lshl_add_u64 v[8:9], v[8:9], 0, v[48:49]
	s_mov_b32 m0, s21
	v_readfirstlane_b32 s21, v200
	global_load_lds_dwordx4 v[8:9], off
	v_lshl_add_u64 v[8:9], s[36:37], 0, v[14:15]
	v_lshl_add_u64 v[8:9], v[8:9], 0, v[48:49]
	s_mov_b32 m0, s21
	v_readfirstlane_b32 s21, v121
	global_load_lds_dwordx4 v[8:9], off
	v_lshl_add_u64 v[8:9], s[34:35], 0, v[16:17]
	v_lshl_add_u64 v[8:9], v[8:9], 0, v[50:51]
	s_mov_b32 m0, s21
	v_readfirstlane_b32 s21, v201
	global_load_lds_dwordx4 v[8:9], off
	v_lshl_add_u64 v[8:9], s[36:37], 0, v[16:17]
	v_lshl_add_u64 v[8:9], v[8:9], 0, v[50:51]
	s_mov_b32 m0, s21
	v_readfirstlane_b32 s21, v122
	global_load_lds_dwordx4 v[8:9], off
	v_lshl_add_u64 v[8:9], s[34:35], 0, v[18:19]
	v_lshl_add_u64 v[8:9], v[8:9], 0, v[52:53]
	s_mov_b32 m0, s21
	v_readfirstlane_b32 s21, v202
	global_load_lds_dwordx4 v[8:9], off
	v_lshl_add_u64 v[8:9], s[36:37], 0, v[18:19]
	v_lshl_add_u64 v[8:9], v[8:9], 0, v[52:53]
	s_mov_b32 m0, s21
	v_readfirstlane_b32 s21, v123
	global_load_lds_dwordx4 v[8:9], off
	v_lshl_add_u64 v[8:9], s[34:35], 0, v[20:21]
	v_lshl_add_u64 v[8:9], v[8:9], 0, v[54:55]
	s_mov_b32 m0, s21
	v_readfirstlane_b32 s21, v203
	global_load_lds_dwordx4 v[8:9], off
	v_lshl_add_u64 v[8:9], s[36:37], 0, v[20:21]
	v_lshl_add_u64 v[8:9], v[8:9], 0, v[54:55]
	s_mov_b32 m0, s21
	v_accvgpr_read_b32 v67, a159
	global_load_lds_dwordx4 v[8:9], off
	s_waitcnt vmcnt(0)
	v_lshl_add_u64 v[68:69], v[24:25], 0, s[0:1]
	v_lshl_add_u64 v[70:71], v[26:27], 0, s[0:1]
	v_lshl_add_u64 v[72:73], v[28:29], 0, s[0:1]
	v_lshl_add_u64 v[74:75], v[30:31], 0, s[0:1]
	v_lshl_add_u64 v[76:77], v[32:33], 0, s[0:1]
	v_lshl_add_u64 v[78:79], v[34:35], 0, s[0:1]
	v_lshl_add_u64 v[80:81], v[36:37], 0, s[0:1]
	v_mov_b32_e32 v83, s1
	v_or_b32_e32 v82, s0, v38
	s_mov_b32 s21, 0
	v_accvgpr_write_b32 a0, 0
	v_accvgpr_mov_b32 a1, a123
	v_accvgpr_mov_b32 a2, a122
	v_accvgpr_mov_b32 a3, a121
	v_accvgpr_mov_b32 a4, a120
	v_accvgpr_mov_b32 a5, a119
	v_accvgpr_mov_b32 a6, a118
	v_accvgpr_mov_b32 a7, a117
	v_accvgpr_mov_b32 a8, a116
	v_accvgpr_mov_b32 a9, a115
	v_accvgpr_mov_b32 a10, a114
	v_accvgpr_mov_b32 a11, a113
	v_accvgpr_mov_b32 a12, a112
	v_accvgpr_mov_b32 a13, a111
	v_accvgpr_mov_b32 a14, a110
	v_accvgpr_mov_b32 a15, a109
	v_accvgpr_write_b32 a16, 0
	v_accvgpr_mov_b32 a17, a108
	v_accvgpr_mov_b32 a18, a107
	v_accvgpr_mov_b32 a19, a106
	v_accvgpr_mov_b32 a20, a105
	v_accvgpr_mov_b32 a21, a104
	v_accvgpr_mov_b32 a22, a103
	v_accvgpr_mov_b32 a23, a102
	v_accvgpr_mov_b32 a24, a101
	v_accvgpr_mov_b32 a25, a100
	v_accvgpr_mov_b32 a26, a99
	v_accvgpr_mov_b32 a27, a98
	v_accvgpr_mov_b32 a28, a97
	v_accvgpr_mov_b32 a29, a96
	v_accvgpr_mov_b32 a30, a95
	v_accvgpr_mov_b32 a31, a94
	v_accvgpr_write_b32 a32, 0
	v_accvgpr_mov_b32 a33, a93
	v_accvgpr_mov_b32 a34, a92
	v_accvgpr_mov_b32 a35, a91
	v_accvgpr_mov_b32 a36, a90
	v_accvgpr_mov_b32 a37, a89
	v_accvgpr_mov_b32 a38, a88
	v_accvgpr_mov_b32 a39, a87
	v_accvgpr_mov_b32 a40, a86
	v_accvgpr_mov_b32 a41, a85
	v_accvgpr_mov_b32 a42, a84
	v_accvgpr_mov_b32 a43, a83
	v_accvgpr_mov_b32 a44, a82
	v_accvgpr_mov_b32 a45, a81
	v_accvgpr_mov_b32 a46, a80
	v_accvgpr_mov_b32 a47, a79
	v_accvgpr_write_b32 a48, 0
	v_accvgpr_mov_b32 a49, a78
	v_accvgpr_mov_b32 a50, a77
	v_accvgpr_mov_b32 a51, a76
	v_accvgpr_mov_b32 a52, a75
	v_accvgpr_mov_b32 a53, a74
	v_accvgpr_mov_b32 a54, a73
	v_accvgpr_mov_b32 a55, a72
	v_accvgpr_mov_b32 a56, a71
	v_accvgpr_mov_b32 a57, a70
	v_accvgpr_mov_b32 a58, a69
	v_accvgpr_mov_b32 a59, a68
	v_accvgpr_mov_b32 a60, a67
	v_accvgpr_mov_b32 a61, a66
	v_accvgpr_mov_b32 a62, a65
	v_accvgpr_mov_b32 a63, a64
	s_waitcnt vmcnt(0) lgkmcnt(0)
	s_barrier
	s_branch .LBB0_1418
